# v7 plus: 8-way sharded deferred-tile counter, XCD-adjacent order of the up GEMM tail tiles, static priority for waves 0-3 in the prompt scans, 3+1 / 5 row split of the final-norm phase
# speedup vs baseline: 1.0027x; 1.0027x over previous
; #define LAS __attribute__((address_space(3)))
; __device__ __forceinline__ int opaque_bid() { int t = blockIdx.x; asm volatile("" : "+s"(t)); return t; }
; __global__ void __launch_bounds__(512, 2) hymba_fwd(Params p0) {
;     ...
;         case 5: if (PH_MASK & 32) { pg8::Gemm g{(const bf16_t*)(p.ws + WS_A2), (const bf16_t*)(p.ws + WS_WUP), MP, N3, 2048}; pg8::StaticOrder S; S.init(MP, N3, gridDim.x, opaque_bid());
;                   Epi3 E{(bf16_t*)(p.ws + WS_UP), (const float*)(p.ws + WS_SS2)}; pg8::gemm_phase((LAS unsigned char*)smem, g, S, E);
;                   convert_in_tail(p, smem, (MP / 256) * (N3 / 256), T_IN + T_OUT + T_UP, T_ALL); } break;
.Lp5_tail_tile:
	s_sub_i32 s9, s14, 0x580
	s_cmpk_ge_u32 s9, 0xd8
	s_cbranch_scc1 .Lp5_tail_perm_done
	s_and_b32 s8, s9, 7
	s_mul_i32 s8, s8, 27
	s_lshr_b32 s9, s9, 3
	s_add_i32 s9, s9, s8
.Lp5_tail_perm_done:
	s_mul_i32 s8, s9, 0xcccd
	s_lshr_b32 s8, s8, 18
	s_mul_i32 s13, s8, 5
	s_sub_i32 s13, s9, s13
	s_add_i32 s12, s13, 32
	s_and_b32 s16, s26, 7
	s_lshl_b32 s16, s16, 6
	s_add_u32 s16, s16, 0x22b32500
	s_add_u32 s16, s82, s16
	s_addc_u32 s17, s83, 0
	s_mov_b32 s9, 0
